# phase_mod main loop: the 14 later weight-row loads of each 16-row batch hoisted to the batch top (one exposed latency per batch instead of three), on top of v008
# baseline (speedup 1.0000x reference)
; __device__ __forceinline__ void phase_mod(const Params& p, unsigned char* lds) {
;     ...
;                 for (int kb = 0; kb < 64; kb += 16) {
;                     float w[16];
; #pragma unroll
;                     for (int u = 0; u < 16; ++u) w[u] = __builtin_nontemporal_load(wp + (size_t)(kb + u) * 6144);
; #pragma unroll
;                     for (int u = 0; u < 16; ++u) { const f32x4* sp = (const f32x4*)(scs + (kq * 64 + kb + u) * 36);
; #pragma unroll
;                         for (int s4 = 0; s4 < 9; ++s4) { const f32x4 sv = sp[s4];
;                             acc[4 * s4 + 0] += sv[0] * w[u]; acc[4 * s4 + 1] += sv[1] * w[u]; acc[4 * s4 + 2] += sv[2] * w[u]; acc[4 * s4 + 3] += sv[3] * w[u]; } }
.LBB0_18:
	global_load_dword v48, v[44:45], off nt
	ds_read_b128 v[58:61], v57
	ds_read_b128 v[62:65], v57 offset:16
	ds_read_b128 v[66:69], v57 offset:32
	v_add_co_u32_e32 v46, vcc, s42, v44
	s_add_i32 s36, s36, 16
	s_nop 0
	v_addc_co_u32_e32 v47, vcc, 0, v45, vcc
	v_add_co_u32_e32 v50, vcc, s57, v44
	s_cmp_lt_u32 s36, 48
	s_nop 0
	v_addc_co_u32_e32 v51, vcc, 0, v45, vcc
	global_load_dword v38, v[50:51], off nt
	v_add_co_u32_e32 v252, vcc, s42, v44
	s_nop 1
	v_addc_co_u32_e32 v253, vcc, 0, v45, vcc
	global_load_dword v234, v[252:253], off nt
	v_add_co_u32_e32 v252, vcc, s44, v44
	s_nop 1
	v_addc_co_u32_e32 v253, vcc, 0, v45, vcc
	global_load_dword v235, v[252:253], off nt
	v_add_co_u32_e32 v252, vcc, s45, v44
	s_nop 1
	v_addc_co_u32_e32 v253, vcc, 0, v45, vcc
	global_load_dword v236, v[252:253], off nt
	v_add_co_u32_e32 v252, vcc, s46, v44
	s_nop 1
	v_addc_co_u32_e32 v253, vcc, 0, v45, vcc
	global_load_dword v237, v[252:253], off nt
	v_add_co_u32_e32 v252, vcc, s47, v44
	s_nop 1
	v_addc_co_u32_e32 v253, vcc, 0, v45, vcc
	global_load_dword v238, v[252:253], off nt
	v_add_co_u32_e32 v252, vcc, s48, v44
	s_nop 1
	v_addc_co_u32_e32 v253, vcc, 0, v45, vcc
	global_load_dword v239, v[252:253], off nt
	v_add_co_u32_e32 v252, vcc, s49, v44
	s_nop 1
	v_addc_co_u32_e32 v253, vcc, 0, v45, vcc
	global_load_dword v240, v[252:253], off nt
	v_add_co_u32_e32 v252, vcc, s50, v44
	s_nop 1
	v_addc_co_u32_e32 v253, vcc, 0, v45, vcc
	global_load_dword v241, v[252:253], off nt
	v_add_co_u32_e32 v252, vcc, s51, v44
	s_nop 1
	v_addc_co_u32_e32 v253, vcc, 0, v45, vcc
	global_load_dword v242, v[252:253], off nt
	v_add_co_u32_e32 v252, vcc, s52, v44
	s_nop 1
	v_addc_co_u32_e32 v253, vcc, 0, v45, vcc
	global_load_dword v243, v[252:253], off nt
	v_add_co_u32_e32 v252, vcc, s53, v44
	s_nop 1
	v_addc_co_u32_e32 v253, vcc, 0, v45, vcc
	global_load_dword v244, v[252:253], off nt
	v_add_co_u32_e32 v252, vcc, s54, v44
	s_nop 1
	v_addc_co_u32_e32 v253, vcc, 0, v45, vcc
	global_load_dword v245, v[252:253], off nt
	v_add_co_u32_e32 v252, vcc, s55, v44
	s_nop 1
	v_addc_co_u32_e32 v253, vcc, 0, v45, vcc
	global_load_dword v250, v[252:253], off nt
	v_add_co_u32_e32 v252, vcc, s56, v44
	s_nop 1
	v_addc_co_u32_e32 v253, vcc, 0, v45, vcc
	global_load_dword v251, v[252:253], off nt
	s_waitcnt vmcnt(15) lgkmcnt(2)
	v_pk_fma_f32 v[34:35], v[48:49], v[58:59], v[34:35] op_sel_hi:[0,1,1]
	v_pk_fma_f32 v[36:37], v[48:49], v[60:61], v[36:37] op_sel_hi:[0,1,1]
	ds_read_b128 v[58:61], v57 offset:48
	s_waitcnt lgkmcnt(2)
	v_pk_fma_f32 v[26:27], v[48:49], v[62:63], v[26:27] op_sel_hi:[0,1,1]
	v_pk_fma_f32 v[28:29], v[48:49], v[64:65], v[28:29] op_sel_hi:[0,1,1]
	ds_read_b128 v[62:65], v57 offset:64
	s_waitcnt lgkmcnt(2)
	v_pk_fma_f32 v[50:51], v[48:49], v[66:67], v[22:23] op_sel_hi:[0,1,1]
	v_pk_fma_f32 v[66:67], v[48:49], v[68:69], v[24:25] op_sel_hi:[0,1,1]
	ds_read_b128 v[22:25], v57 offset:80
	s_waitcnt lgkmcnt(2)
	v_pk_fma_f32 v[58:59], v[48:49], v[58:59], v[10:11] op_sel_hi:[0,1,1]
	v_pk_fma_f32 v[60:61], v[48:49], v[60:61], v[12:13] op_sel_hi:[0,1,1]
	ds_read_b128 v[10:13], v57 offset:96
	s_waitcnt lgkmcnt(2)
	v_pk_fma_f32 v[62:63], v[48:49], v[62:63], v[14:15] op_sel_hi:[0,1,1]
	v_pk_fma_f32 v[64:65], v[48:49], v[64:65], v[16:17] op_sel_hi:[0,1,1]
	ds_read_b128 v[14:17], v57 offset:112
	v_add_co_u32_e32 v68, vcc, s44, v44
	s_waitcnt lgkmcnt(1)
	v_pk_fma_f32 v[18:19], v[48:49], v[10:11], v[18:19] op_sel_hi:[0,1,1]
	v_pk_fma_f32 v[20:21], v[48:49], v[12:13], v[20:21] op_sel_hi:[0,1,1]
	ds_read_b128 v[10:13], v57 offset:128
	v_addc_co_u32_e32 v69, vcc, 0, v45, vcc
	v_pk_fma_f32 v[22:23], v[48:49], v[22:23], v[30:31] op_sel_hi:[0,1,1]
	v_add_co_u32_e32 v30, vcc, s45, v44
	s_waitcnt lgkmcnt(0)
	v_pk_fma_f32 v[72:73], v[48:49], v[10:11], v[2:3] op_sel_hi:[0,1,1]
	v_addc_co_u32_e32 v31, vcc, 0, v45, vcc
	v_add_co_u32_e32 v2, vcc, s46, v44
	v_pk_fma_f32 v[24:25], v[48:49], v[24:25], v[32:33] op_sel_hi:[0,1,1]
	s_nop 0
	v_addc_co_u32_e32 v3, vcc, 0, v45, vcc
	v_pk_fma_f32 v[32:33], v[48:49], v[14:15], v[6:7] op_sel_hi:[0,1,1]
	v_pk_fma_f32 v[70:71], v[48:49], v[16:17], v[8:9] op_sel_hi:[0,1,1]
	v_pk_fma_f32 v[48:49], v[48:49], v[12:13], v[4:5] op_sel_hi:[0,1,1]
	v_add_co_u32_e32 v4, vcc, s47, v44
	ds_read_b128 v[14:17], v57 offset:144
	s_nop 0
	v_addc_co_u32_e32 v5, vcc, 0, v45, vcc
	v_add_co_u32_e32 v6, vcc, s48, v44
	s_nop 1
	v_addc_co_u32_e32 v7, vcc, 0, v45, vcc
	v_add_co_u32_e32 v10, vcc, s49, v44
	s_nop 1
	v_addc_co_u32_e32 v11, vcc, 0, v45, vcc
	v_add_co_u32_e32 v12, vcc, s50, v44
	s_nop 1
	v_addc_co_u32_e32 v13, vcc, 0, v45, vcc
	s_waitcnt vmcnt(6)
	v_mov_b32_e32 v46, v234
	s_nop 0
	v_mov_b32_e32 v68, v235
	s_nop 0
	v_mov_b32_e32 v30, v236
	s_nop 0
	v_mov_b32_e32 v74, v237
	v_mov_b32_e32 v8, v238
	s_nop 0
	v_mov_b32_e32 v6, v239
	s_nop 0
	v_mov_b32_e32 v4, v240
	v_mov_b32_e32 v2, v241
	s_waitcnt vmcnt(7) lgkmcnt(0)
	v_pk_fma_f32 v[34:35], v[46:47], v[14:15], v[34:35] op_sel_hi:[0,1,1]
	v_pk_fma_f32 v[36:37], v[46:47], v[16:17], v[36:37] op_sel_hi:[0,1,1]
	ds_read_b128 v[10:13], v57 offset:160
	ds_read_b128 v[14:17], v57 offset:176
	s_waitcnt lgkmcnt(1)
	v_pk_fma_f32 v[26:27], v[46:47], v[10:11], v[26:27] op_sel_hi:[0,1,1]
	v_pk_fma_f32 v[28:29], v[46:47], v[12:13], v[28:29] op_sel_hi:[0,1,1]
	s_waitcnt lgkmcnt(0)
	v_pk_fma_f32 v[50:51], v[46:47], v[14:15], v[50:51] op_sel_hi:[0,1,1]
	v_pk_fma_f32 v[66:67], v[46:47], v[16:17], v[66:67] op_sel_hi:[0,1,1]
	ds_read_b128 v[10:13], v57 offset:192
	ds_read_b128 v[14:17], v57 offset:208
	s_waitcnt lgkmcnt(1)
	v_pk_fma_f32 v[58:59], v[46:47], v[10:11], v[58:59] op_sel_hi:[0,1,1]
	v_pk_fma_f32 v[60:61], v[46:47], v[12:13], v[60:61] op_sel_hi:[0,1,1]
	s_waitcnt lgkmcnt(0)
; __device__ __forceinline__ void phase_mod(const Params& p, unsigned char* lds) {
;     ...
;                     for (int u = 0; u < 16; ++u) { const f32x4* sp = (const f32x4*)(scs + (kq * 64 + kb + u) * 36);
; #pragma unroll
;                         for (int s4 = 0; s4 < 9; ++s4) { const f32x4 sv = sp[s4];
;                             acc[4 * s4 + 0] += sv[0] * w[u]; acc[4 * s4 + 1] += sv[1] * w[u]; acc[4 * s4 + 2] += sv[2] * w[u]; acc[4 * s4 + 3] += sv[3] * w[u]; } }
	v_pk_fma_f32 v[62:63], v[46:47], v[14:15], v[62:63] op_sel_hi:[0,1,1]
	v_pk_fma_f32 v[64:65], v[46:47], v[16:17], v[64:65] op_sel_hi:[0,1,1]
	ds_read_b128 v[10:13], v57 offset:224
	ds_read_b128 v[14:17], v57 offset:240
	s_waitcnt lgkmcnt(1)
	v_pk_fma_f32 v[22:23], v[46:47], v[10:11], v[22:23] op_sel_hi:[0,1,1]
	v_pk_fma_f32 v[24:25], v[46:47], v[12:13], v[24:25] op_sel_hi:[0,1,1]
	s_waitcnt lgkmcnt(0)
	v_pk_fma_f32 v[18:19], v[46:47], v[14:15], v[18:19] op_sel_hi:[0,1,1]
	v_pk_fma_f32 v[20:21], v[46:47], v[16:17], v[20:21] op_sel_hi:[0,1,1]
	ds_read_b128 v[10:13], v57 offset:256
	ds_read_b128 v[14:17], v57 offset:272
	s_waitcnt lgkmcnt(1)
	v_pk_fma_f32 v[32:33], v[46:47], v[10:11], v[32:33] op_sel_hi:[0,1,1]
	v_pk_fma_f32 v[70:71], v[46:47], v[12:13], v[70:71] op_sel_hi:[0,1,1]
	s_waitcnt lgkmcnt(0)
	v_pk_fma_f32 v[72:73], v[46:47], v[14:15], v[72:73] op_sel_hi:[0,1,1]
	v_pk_fma_f32 v[46:47], v[46:47], v[16:17], v[48:49] op_sel_hi:[0,1,1]
	ds_read_b128 v[10:13], v57 offset:288
	ds_read_b128 v[14:17], v57 offset:304
	s_waitcnt vmcnt(6) lgkmcnt(1)
	v_pk_fma_f32 v[34:35], v[68:69], v[10:11], v[34:35] op_sel_hi:[0,1,1]
	v_pk_fma_f32 v[36:37], v[68:69], v[12:13], v[36:37] op_sel_hi:[0,1,1]
	s_waitcnt lgkmcnt(0)
	v_pk_fma_f32 v[26:27], v[68:69], v[14:15], v[26:27] op_sel_hi:[0,1,1]
	v_pk_fma_f32 v[28:29], v[68:69], v[16:17], v[28:29] op_sel_hi:[0,1,1]
	ds_read_b128 v[10:13], v57 offset:320
	ds_read_b128 v[14:17], v57 offset:336
	s_waitcnt lgkmcnt(1)
	v_pk_fma_f32 v[48:49], v[68:69], v[10:11], v[50:51] op_sel_hi:[0,1,1]
	v_pk_fma_f32 v[50:51], v[68:69], v[12:13], v[66:67] op_sel_hi:[0,1,1]
	s_waitcnt lgkmcnt(0)
	v_pk_fma_f32 v[58:59], v[68:69], v[14:15], v[58:59] op_sel_hi:[0,1,1]
	v_pk_fma_f32 v[60:61], v[68:69], v[16:17], v[60:61] op_sel_hi:[0,1,1]
	ds_read_b128 v[10:13], v57 offset:352
	ds_read_b128 v[14:17], v57 offset:368
	s_waitcnt lgkmcnt(1)
	v_pk_fma_f32 v[62:63], v[68:69], v[10:11], v[62:63] op_sel_hi:[0,1,1]
	v_pk_fma_f32 v[64:65], v[68:69], v[12:13], v[64:65] op_sel_hi:[0,1,1]
	s_waitcnt lgkmcnt(0)
	v_pk_fma_f32 v[22:23], v[68:69], v[14:15], v[22:23] op_sel_hi:[0,1,1]
	v_pk_fma_f32 v[24:25], v[68:69], v[16:17], v[24:25] op_sel_hi:[0,1,1]
	ds_read_b128 v[10:13], v57 offset:384
	ds_read_b128 v[14:17], v57 offset:400
	s_waitcnt lgkmcnt(1)
	v_pk_fma_f32 v[18:19], v[68:69], v[10:11], v[18:19] op_sel_hi:[0,1,1]
	v_pk_fma_f32 v[20:21], v[68:69], v[12:13], v[20:21] op_sel_hi:[0,1,1]
	s_waitcnt lgkmcnt(0)
	v_pk_fma_f32 v[32:33], v[68:69], v[14:15], v[32:33] op_sel_hi:[0,1,1]
	v_pk_fma_f32 v[66:67], v[68:69], v[16:17], v[70:71] op_sel_hi:[0,1,1]
	ds_read_b128 v[10:13], v57 offset:416
	ds_read_b128 v[14:17], v57 offset:432
	s_waitcnt lgkmcnt(1)
	v_pk_fma_f32 v[70:71], v[68:69], v[10:11], v[72:73] op_sel_hi:[0,1,1]
	v_pk_fma_f32 v[46:47], v[68:69], v[12:13], v[46:47] op_sel_hi:[0,1,1]
	s_waitcnt vmcnt(5) lgkmcnt(0)
	v_pk_fma_f32 v[34:35], v[30:31], v[14:15], v[34:35] op_sel_hi:[0,1,1]
	v_pk_fma_f32 v[36:37], v[30:31], v[16:17], v[36:37] op_sel_hi:[0,1,1]
	ds_read_b128 v[10:13], v57 offset:448
	ds_read_b128 v[14:17], v57 offset:464
	s_waitcnt lgkmcnt(1)
	v_pk_fma_f32 v[26:27], v[30:31], v[10:11], v[26:27] op_sel_hi:[0,1,1]
	v_pk_fma_f32 v[28:29], v[30:31], v[12:13], v[28:29] op_sel_hi:[0,1,1]
	s_waitcnt lgkmcnt(0)
	v_pk_fma_f32 v[48:49], v[30:31], v[14:15], v[48:49] op_sel_hi:[0,1,1]
	v_pk_fma_f32 v[50:51], v[30:31], v[16:17], v[50:51] op_sel_hi:[0,1,1]
	ds_read_b128 v[10:13], v57 offset:480
	ds_read_b128 v[14:17], v57 offset:496
	s_waitcnt lgkmcnt(1)
	v_pk_fma_f32 v[58:59], v[30:31], v[10:11], v[58:59] op_sel_hi:[0,1,1]
	v_pk_fma_f32 v[60:61], v[30:31], v[12:13], v[60:61] op_sel_hi:[0,1,1]
	s_waitcnt lgkmcnt(0)
	v_pk_fma_f32 v[62:63], v[30:31], v[14:15], v[62:63] op_sel_hi:[0,1,1]
	v_pk_fma_f32 v[64:65], v[30:31], v[16:17], v[64:65] op_sel_hi:[0,1,1]
	ds_read_b128 v[10:13], v57 offset:512
	ds_read_b128 v[14:17], v57 offset:528
	s_waitcnt lgkmcnt(1)
	v_pk_fma_f32 v[22:23], v[30:31], v[10:11], v[22:23] op_sel_hi:[0,1,1]
	v_pk_fma_f32 v[24:25], v[30:31], v[12:13], v[24:25] op_sel_hi:[0,1,1]
	s_waitcnt lgkmcnt(0)
	v_pk_fma_f32 v[18:19], v[30:31], v[14:15], v[18:19] op_sel_hi:[0,1,1]
	v_pk_fma_f32 v[20:21], v[30:31], v[16:17], v[20:21] op_sel_hi:[0,1,1]
	ds_read_b128 v[10:13], v57 offset:544
	ds_read_b128 v[14:17], v57 offset:560
	s_waitcnt lgkmcnt(1)
	v_pk_fma_f32 v[32:33], v[30:31], v[10:11], v[32:33] op_sel_hi:[0,1,1]
	v_pk_fma_f32 v[66:67], v[30:31], v[12:13], v[66:67] op_sel_hi:[0,1,1]
	s_waitcnt lgkmcnt(0)
	v_pk_fma_f32 v[68:69], v[30:31], v[14:15], v[70:71] op_sel_hi:[0,1,1]
	v_pk_fma_f32 v[30:31], v[30:31], v[16:17], v[46:47] op_sel_hi:[0,1,1]
	ds_read_b128 v[10:13], v57 offset:576
	ds_read_b128 v[14:17], v57 offset:592
	s_waitcnt vmcnt(4) lgkmcnt(1)
	v_pk_fma_f32 v[34:35], v[74:75], v[10:11], v[34:35] op_sel_hi:[0,1,1]
	v_pk_fma_f32 v[36:37], v[74:75], v[12:13], v[36:37] op_sel_hi:[0,1,1]
	ds_read_b128 v[10:13], v57 offset:608
	s_waitcnt lgkmcnt(1)
	v_pk_fma_f32 v[26:27], v[74:75], v[14:15], v[26:27] op_sel_hi:[0,1,1]
	v_pk_fma_f32 v[28:29], v[74:75], v[16:17], v[28:29] op_sel_hi:[0,1,1]
	ds_read_b128 v[14:17], v57 offset:624
	s_waitcnt lgkmcnt(1)
	v_pk_fma_f32 v[46:47], v[74:75], v[10:11], v[48:49] op_sel_hi:[0,1,1]
	v_pk_fma_f32 v[48:49], v[74:75], v[12:13], v[50:51] op_sel_hi:[0,1,1]
	ds_read_b128 v[10:13], v57 offset:640
	s_waitcnt lgkmcnt(1)
	v_pk_fma_f32 v[50:51], v[74:75], v[14:15], v[58:59] op_sel_hi:[0,1,1]
	v_pk_fma_f32 v[58:59], v[74:75], v[16:17], v[60:61] op_sel_hi:[0,1,1]
	ds_read_b128 v[14:17], v57 offset:656
	s_waitcnt lgkmcnt(1)
; __device__ __forceinline__ void phase_mod(const Params& p, unsigned char* lds) {
;     ...
;                     for (int u = 0; u < 16; ++u) { const f32x4* sp = (const f32x4*)(scs + (kq * 64 + kb + u) * 36);
; #pragma unroll
;                         for (int s4 = 0; s4 < 9; ++s4) { const f32x4 sv = sp[s4];
;                             acc[4 * s4 + 0] += sv[0] * w[u]; acc[4 * s4 + 1] += sv[1] * w[u]; acc[4 * s4 + 2] += sv[2] * w[u]; acc[4 * s4 + 3] += sv[3] * w[u]; } }
	v_pk_fma_f32 v[60:61], v[74:75], v[10:11], v[62:63] op_sel_hi:[0,1,1]
	v_pk_fma_f32 v[62:63], v[74:75], v[12:13], v[64:65] op_sel_hi:[0,1,1]
	ds_read_b128 v[10:13], v57 offset:672
	s_waitcnt lgkmcnt(1)
	v_pk_fma_f32 v[22:23], v[74:75], v[14:15], v[22:23] op_sel_hi:[0,1,1]
	v_pk_fma_f32 v[24:25], v[74:75], v[16:17], v[24:25] op_sel_hi:[0,1,1]
	ds_read_b128 v[14:17], v57 offset:688
	s_waitcnt lgkmcnt(1)
	v_pk_fma_f32 v[18:19], v[74:75], v[10:11], v[18:19] op_sel_hi:[0,1,1]
	v_pk_fma_f32 v[64:65], v[74:75], v[12:13], v[20:21] op_sel_hi:[0,1,1]
	ds_read_b128 v[10:13], v57 offset:704
	s_waitcnt lgkmcnt(1)
	v_pk_fma_f32 v[32:33], v[74:75], v[14:15], v[32:33] op_sel_hi:[0,1,1]
	v_pk_fma_f32 v[66:67], v[74:75], v[16:17], v[66:67] op_sel_hi:[0,1,1]
	ds_read_b128 v[14:17], v57 offset:720
	s_waitcnt lgkmcnt(1)
	v_pk_fma_f32 v[68:69], v[74:75], v[10:11], v[68:69] op_sel_hi:[0,1,1]
	v_pk_fma_f32 v[70:71], v[74:75], v[12:13], v[30:31] op_sel_hi:[0,1,1]
	ds_read_b128 v[10:13], v57 offset:736
	s_waitcnt vmcnt(3) lgkmcnt(1)
	v_pk_fma_f32 v[72:73], v[8:9], v[14:15], v[34:35] op_sel_hi:[0,1,1]
	v_pk_fma_f32 v[74:75], v[8:9], v[16:17], v[36:37] op_sel_hi:[0,1,1]
	ds_read_b128 v[14:17], v57 offset:752
	s_waitcnt lgkmcnt(1)
	v_pk_fma_f32 v[76:77], v[8:9], v[10:11], v[26:27] op_sel_hi:[0,1,1]
	v_pk_fma_f32 v[78:79], v[8:9], v[12:13], v[28:29] op_sel_hi:[0,1,1]
	ds_read_b128 v[10:13], v57 offset:768
	s_waitcnt lgkmcnt(1)
	v_pk_fma_f32 v[80:81], v[8:9], v[14:15], v[46:47] op_sel_hi:[0,1,1]
	v_pk_fma_f32 v[82:83], v[8:9], v[16:17], v[48:49] op_sel_hi:[0,1,1]
	ds_read_b128 v[14:17], v57 offset:784
	s_waitcnt lgkmcnt(1)
	v_pk_fma_f32 v[48:49], v[8:9], v[10:11], v[50:51] op_sel_hi:[0,1,1]
	v_pk_fma_f32 v[50:51], v[8:9], v[12:13], v[58:59] op_sel_hi:[0,1,1]
	ds_read_b128 v[10:13], v57 offset:800
	s_waitcnt lgkmcnt(1)
	v_pk_fma_f32 v[36:37], v[8:9], v[14:15], v[60:61] op_sel_hi:[0,1,1]
	v_pk_fma_f32 v[46:47], v[8:9], v[16:17], v[62:63] op_sel_hi:[0,1,1]
	ds_read_b128 v[14:17], v57 offset:816
	s_waitcnt lgkmcnt(1)
	v_pk_fma_f32 v[28:29], v[8:9], v[10:11], v[22:23] op_sel_hi:[0,1,1]
	v_pk_fma_f32 v[30:31], v[8:9], v[12:13], v[24:25] op_sel_hi:[0,1,1]
	ds_read_b128 v[10:13], v57 offset:832
	ds_read_b128 v[24:27], v57 offset:848
	s_waitcnt lgkmcnt(2)
	v_pk_fma_f32 v[20:21], v[8:9], v[14:15], v[18:19] op_sel_hi:[0,1,1]
	v_pk_fma_f32 v[22:23], v[8:9], v[16:17], v[64:65] op_sel_hi:[0,1,1]
	s_waitcnt lgkmcnt(1)
	v_pk_fma_f32 v[16:17], v[8:9], v[10:11], v[32:33] op_sel_hi:[0,1,1]
	v_pk_fma_f32 v[18:19], v[8:9], v[12:13], v[66:67] op_sel_hi:[0,1,1]
	ds_read_b128 v[32:35], v57 offset:864
	s_waitcnt lgkmcnt(1)
	v_pk_fma_f32 v[12:13], v[8:9], v[24:25], v[68:69] op_sel_hi:[0,1,1]
	v_pk_fma_f32 v[14:15], v[8:9], v[26:27], v[70:71] op_sel_hi:[0,1,1]
	ds_read_b128 v[24:27], v57 offset:880
	ds_read_b128 v[58:61], v57 offset:896
	ds_read_b128 v[62:65], v57 offset:912
	ds_read_b128 v[66:69], v57 offset:928
	s_waitcnt vmcnt(2) lgkmcnt(4)
	v_pk_fma_f32 v[8:9], v[6:7], v[32:33], v[72:73] op_sel_hi:[0,1,1]
	v_pk_fma_f32 v[10:11], v[6:7], v[34:35], v[74:75] op_sel_hi:[0,1,1]
	s_waitcnt lgkmcnt(2)
	v_pk_fma_f32 v[32:33], v[6:7], v[58:59], v[80:81] op_sel_hi:[0,1,1]
	v_pk_fma_f32 v[34:35], v[6:7], v[60:61], v[82:83] op_sel_hi:[0,1,1]
	ds_read_b128 v[58:61], v57 offset:944
	s_waitcnt lgkmcnt(1)
	v_pk_fma_f32 v[36:37], v[6:7], v[66:67], v[36:37] op_sel_hi:[0,1,1]
	v_pk_fma_f32 v[46:47], v[6:7], v[68:69], v[46:47] op_sel_hi:[0,1,1]
	ds_read_b128 v[66:69], v57 offset:976
	v_pk_fma_f32 v[48:49], v[6:7], v[62:63], v[48:49] op_sel_hi:[0,1,1]
	v_pk_fma_f32 v[50:51], v[6:7], v[64:65], v[50:51] op_sel_hi:[0,1,1]
	ds_read_b128 v[62:65], v57 offset:960
	s_waitcnt lgkmcnt(2)
	v_pk_fma_f32 v[58:59], v[6:7], v[58:59], v[28:29] op_sel_hi:[0,1,1]
	v_pk_fma_f32 v[60:61], v[6:7], v[60:61], v[30:31] op_sel_hi:[0,1,1]
	ds_read_b128 v[28:31], v57 offset:992
	s_waitcnt lgkmcnt(2)
	v_pk_fma_f32 v[66:67], v[6:7], v[66:67], v[16:17] op_sel_hi:[0,1,1]
	v_pk_fma_f32 v[68:69], v[6:7], v[68:69], v[18:19] op_sel_hi:[0,1,1]
	ds_read_b128 v[16:19], v57 offset:1008
	v_pk_fma_f32 v[24:25], v[6:7], v[24:25], v[76:77] op_sel_hi:[0,1,1]
	v_pk_fma_f32 v[26:27], v[6:7], v[26:27], v[78:79] op_sel_hi:[0,1,1]
	s_waitcnt lgkmcnt(2)
	v_pk_fma_f32 v[62:63], v[6:7], v[62:63], v[20:21] op_sel_hi:[0,1,1]
	v_pk_fma_f32 v[64:65], v[6:7], v[64:65], v[22:23] op_sel_hi:[0,1,1]
	s_waitcnt lgkmcnt(1)
	v_pk_fma_f32 v[28:29], v[6:7], v[28:29], v[12:13] op_sel_hi:[0,1,1]
	v_pk_fma_f32 v[30:31], v[6:7], v[30:31], v[14:15] op_sel_hi:[0,1,1]
	ds_read_b128 v[12:15], v57 offset:1024
	ds_read_b128 v[20:23], v57 offset:1040
	s_waitcnt vmcnt(1) lgkmcnt(2)
	v_pk_fma_f32 v[72:73], v[4:5], v[16:17], v[8:9] op_sel_hi:[0,1,1]
	ds_read_b128 v[6:9], v57 offset:1056
	v_pk_fma_f32 v[18:19], v[4:5], v[18:19], v[10:11] op_sel_hi:[0,1,1]
	s_waitcnt lgkmcnt(2)
	v_pk_fma_f32 v[24:25], v[4:5], v[12:13], v[24:25] op_sel_hi:[0,1,1]
	v_pk_fma_f32 v[26:27], v[4:5], v[14:15], v[26:27] op_sel_hi:[0,1,1]
	ds_read_b128 v[10:13], v57 offset:1072
	s_waitcnt lgkmcnt(2)
	v_pk_fma_f32 v[20:21], v[4:5], v[20:21], v[32:33] op_sel_hi:[0,1,1]
	v_pk_fma_f32 v[22:23], v[4:5], v[22:23], v[34:35] op_sel_hi:[0,1,1]
	ds_read_b128 v[14:17], v57 offset:1088
	s_waitcnt lgkmcnt(2)
	v_pk_fma_f32 v[32:33], v[4:5], v[6:7], v[48:49] op_sel_hi:[0,1,1]
	v_pk_fma_f32 v[34:35], v[4:5], v[8:9], v[50:51] op_sel_hi:[0,1,1]
	ds_read_b128 v[6:9], v57 offset:1104
	s_waitcnt lgkmcnt(2)
	v_pk_fma_f32 v[36:37], v[4:5], v[10:11], v[36:37] op_sel_hi:[0,1,1]
	v_pk_fma_f32 v[46:47], v[4:5], v[12:13], v[46:47] op_sel_hi:[0,1,1]
	ds_read_b128 v[10:13], v57 offset:1120
	s_waitcnt lgkmcnt(2)
; __device__ __forceinline__ void phase_mod(const Params& p, unsigned char* lds) {
;     ...
;                 for (int kb = 0; kb < 64; kb += 16) {
;                     float w[16];
; #pragma unroll
;                     for (int u = 0; u < 16; ++u) w[u] = __builtin_nontemporal_load(wp + (size_t)(kb + u) * 6144);
; #pragma unroll
;                     for (int u = 0; u < 16; ++u) { const f32x4* sp = (const f32x4*)(scs + (kq * 64 + kb + u) * 36);
; #pragma unroll
;                         for (int s4 = 0; s4 < 9; ++s4) { const f32x4 sv = sp[s4];
;                             acc[4 * s4 + 0] += sv[0] * w[u]; acc[4 * s4 + 1] += sv[1] * w[u]; acc[4 * s4 + 2] += sv[2] * w[u]; acc[4 * s4 + 3] += sv[3] * w[u]; } }
	v_pk_fma_f32 v[48:49], v[4:5], v[14:15], v[58:59] op_sel_hi:[0,1,1]
	v_pk_fma_f32 v[50:51], v[4:5], v[16:17], v[60:61] op_sel_hi:[0,1,1]
	ds_read_b128 v[14:17], v57 offset:1136
	s_waitcnt lgkmcnt(2)
	v_pk_fma_f32 v[58:59], v[4:5], v[6:7], v[62:63] op_sel_hi:[0,1,1]
	v_pk_fma_f32 v[60:61], v[4:5], v[8:9], v[64:65] op_sel_hi:[0,1,1]
	ds_read_b128 v[6:9], v57 offset:1152
	s_waitcnt lgkmcnt(2)
	v_pk_fma_f32 v[64:65], v[4:5], v[10:11], v[66:67] op_sel_hi:[0,1,1]
	v_pk_fma_f32 v[66:67], v[4:5], v[12:13], v[68:69] op_sel_hi:[0,1,1]
	s_waitcnt lgkmcnt(1)
	v_pk_fma_f32 v[28:29], v[4:5], v[14:15], v[28:29] op_sel_hi:[0,1,1]
	v_pk_fma_f32 v[30:31], v[4:5], v[16:17], v[30:31] op_sel_hi:[0,1,1]
	ds_read_b128 v[10:13], v57 offset:1168
	ds_read_b128 v[14:17], v57 offset:1184
	s_waitcnt vmcnt(0) lgkmcnt(2)
	v_pk_fma_f32 v[68:69], v[2:3], v[6:7], v[72:73] op_sel_hi:[0,1,1]
	ds_read_b128 v[4:7], v57 offset:1200
	v_pk_fma_f32 v[18:19], v[2:3], v[8:9], v[18:19] op_sel_hi:[0,1,1]
	s_waitcnt lgkmcnt(2)
	v_pk_fma_f32 v[24:25], v[2:3], v[10:11], v[24:25] op_sel_hi:[0,1,1]
	v_pk_fma_f32 v[26:27], v[2:3], v[12:13], v[26:27] op_sel_hi:[0,1,1]
	ds_read_b128 v[8:11], v57 offset:1216
	s_waitcnt lgkmcnt(2)
	v_pk_fma_f32 v[20:21], v[2:3], v[14:15], v[20:21] op_sel_hi:[0,1,1]
	v_pk_fma_f32 v[16:17], v[2:3], v[16:17], v[22:23] op_sel_hi:[0,1,1]
	ds_read_b128 v[12:15], v57 offset:1232
	s_waitcnt lgkmcnt(2)
	v_pk_fma_f32 v[22:23], v[2:3], v[4:5], v[32:33] op_sel_hi:[0,1,1]
	v_pk_fma_f32 v[32:33], v[2:3], v[6:7], v[34:35] op_sel_hi:[0,1,1]
	ds_read_b128 v[4:7], v57 offset:1248
	v_add_co_u32_e32 v70, vcc, s51, v44
	s_waitcnt lgkmcnt(2)
	v_pk_fma_f32 v[34:35], v[2:3], v[8:9], v[36:37] op_sel_hi:[0,1,1]
	v_addc_co_u32_e32 v71, vcc, 0, v45, vcc
	v_add_co_u32_e32 v62, vcc, s52, v44
	v_pk_fma_f32 v[36:37], v[2:3], v[10:11], v[46:47] op_sel_hi:[0,1,1]
	s_nop 0
	v_addc_co_u32_e32 v63, vcc, 0, v45, vcc
	ds_read_b128 v[8:11], v57 offset:1264
	s_waitcnt lgkmcnt(1)
	v_pk_fma_f32 v[58:59], v[2:3], v[4:5], v[58:59] op_sel_hi:[0,1,1]
	v_pk_fma_f32 v[60:61], v[2:3], v[6:7], v[60:61] op_sel_hi:[0,1,1]
	ds_read_b128 v[4:7], v57 offset:1280
	v_add_co_u32_e32 v46, vcc, s53, v44
	v_pk_fma_f32 v[48:49], v[2:3], v[12:13], v[48:49] op_sel_hi:[0,1,1]
	s_nop 0
	v_addc_co_u32_e32 v47, vcc, 0, v45, vcc
	v_add_co_u32_e32 v12, vcc, s54, v44
	v_pk_fma_f32 v[50:51], v[2:3], v[14:15], v[50:51] op_sel_hi:[0,1,1]
	s_nop 0
	v_addc_co_u32_e32 v13, vcc, 0, v45, vcc
	s_waitcnt lgkmcnt(1)
	v_pk_fma_f32 v[64:65], v[2:3], v[8:9], v[64:65] op_sel_hi:[0,1,1]
	v_pk_fma_f32 v[66:67], v[2:3], v[10:11], v[66:67] op_sel_hi:[0,1,1]
	s_waitcnt lgkmcnt(0)
	v_pk_fma_f32 v[28:29], v[2:3], v[4:5], v[28:29] op_sel_hi:[0,1,1]
	v_pk_fma_f32 v[30:31], v[2:3], v[6:7], v[30:31] op_sel_hi:[0,1,1]
	v_add_co_u32_e32 v2, vcc, s55, v44
	ds_read_b128 v[8:11], v57 offset:1296
	s_nop 0
	v_addc_co_u32_e32 v3, vcc, 0, v45, vcc
	v_add_co_u32_e32 v14, vcc, s56, v44
	s_nop 1
	v_addc_co_u32_e32 v15, vcc, 0, v45, vcc
	s_waitcnt vmcnt(0)
	v_mov_b32_e32 v70, v242
	s_nop 0
	v_mov_b32_e32 v62, v243
	s_nop 0
	v_mov_b32_e32 v46, v244
	s_nop 0
	v_mov_b32_e32 v6, v245
	v_mov_b32_e32 v4, v250
	s_nop 0
	v_mov_b32_e32 v2, v251
	v_lshl_add_u64 v[44:45], v[44:45], 0, s[10:11]
	s_waitcnt vmcnt(5) lgkmcnt(0)
	v_pk_fma_f32 v[68:69], v[70:71], v[8:9], v[68:69] op_sel_hi:[0,1,1]
	v_pk_fma_f32 v[18:19], v[70:71], v[10:11], v[18:19] op_sel_hi:[0,1,1]
	ds_read_b128 v[8:11], v57 offset:1312
	ds_read_b128 v[12:15], v57 offset:1328
	s_waitcnt lgkmcnt(1)
	v_pk_fma_f32 v[24:25], v[70:71], v[8:9], v[24:25] op_sel_hi:[0,1,1]
	v_pk_fma_f32 v[26:27], v[70:71], v[10:11], v[26:27] op_sel_hi:[0,1,1]
	s_waitcnt lgkmcnt(0)
	v_pk_fma_f32 v[20:21], v[70:71], v[12:13], v[20:21] op_sel_hi:[0,1,1]
	v_pk_fma_f32 v[16:17], v[70:71], v[14:15], v[16:17] op_sel_hi:[0,1,1]
	ds_read_b128 v[8:11], v57 offset:1344
	ds_read_b128 v[12:15], v57 offset:1360
	s_waitcnt lgkmcnt(1)
	v_pk_fma_f32 v[22:23], v[70:71], v[8:9], v[22:23] op_sel_hi:[0,1,1]
	v_pk_fma_f32 v[32:33], v[70:71], v[10:11], v[32:33] op_sel_hi:[0,1,1]
	s_waitcnt lgkmcnt(0)
	v_pk_fma_f32 v[34:35], v[70:71], v[12:13], v[34:35] op_sel_hi:[0,1,1]
	v_pk_fma_f32 v[36:37], v[70:71], v[14:15], v[36:37] op_sel_hi:[0,1,1]
	ds_read_b128 v[8:11], v57 offset:1376
	ds_read_b128 v[12:15], v57 offset:1392
	s_waitcnt lgkmcnt(1)
	v_pk_fma_f32 v[48:49], v[70:71], v[8:9], v[48:49] op_sel_hi:[0,1,1]
	v_pk_fma_f32 v[50:51], v[70:71], v[10:11], v[50:51] op_sel_hi:[0,1,1]
	s_waitcnt lgkmcnt(0)
	v_pk_fma_f32 v[58:59], v[70:71], v[12:13], v[58:59] op_sel_hi:[0,1,1]
	v_pk_fma_f32 v[60:61], v[70:71], v[14:15], v[60:61] op_sel_hi:[0,1,1]
	ds_read_b128 v[8:11], v57 offset:1408
	ds_read_b128 v[12:15], v57 offset:1424
	s_waitcnt lgkmcnt(1)
	v_pk_fma_f32 v[64:65], v[70:71], v[8:9], v[64:65] op_sel_hi:[0,1,1]
	v_pk_fma_f32 v[66:67], v[70:71], v[10:11], v[66:67] op_sel_hi:[0,1,1]
	s_waitcnt lgkmcnt(0)
	v_pk_fma_f32 v[28:29], v[70:71], v[12:13], v[28:29] op_sel_hi:[0,1,1]
	v_pk_fma_f32 v[30:31], v[70:71], v[14:15], v[30:31] op_sel_hi:[0,1,1]
	ds_read_b128 v[8:11], v57 offset:1440
	ds_read_b128 v[12:15], v57 offset:1456
	s_waitcnt vmcnt(4) lgkmcnt(1)
	v_pk_fma_f32 v[68:69], v[62:63], v[8:9], v[68:69] op_sel_hi:[0,1,1]
	v_pk_fma_f32 v[18:19], v[62:63], v[10:11], v[18:19] op_sel_hi:[0,1,1]
	ds_read_b128 v[8:11], v57 offset:1472
	s_waitcnt lgkmcnt(1)
	v_pk_fma_f32 v[24:25], v[62:63], v[12:13], v[24:25] op_sel_hi:[0,1,1]
	v_pk_fma_f32 v[26:27], v[62:63], v[14:15], v[26:27] op_sel_hi:[0,1,1]
	ds_read_b128 v[12:15], v57 offset:1488
	s_waitcnt lgkmcnt(1)
	v_pk_fma_f32 v[20:21], v[62:63], v[8:9], v[20:21] op_sel_hi:[0,1,1]
	v_pk_fma_f32 v[16:17], v[62:63], v[10:11], v[16:17] op_sel_hi:[0,1,1]
	ds_read_b128 v[8:11], v57 offset:1504
	s_waitcnt lgkmcnt(1)
; __device__ __forceinline__ void phase_mod(const Params& p, unsigned char* lds) {
;     ...
;                 for (int kb = 0; kb < 64; kb += 16) {
;                     float w[16];
; #pragma unroll
;                     for (int u = 0; u < 16; ++u) w[u] = __builtin_nontemporal_load(wp + (size_t)(kb + u) * 6144);
; #pragma unroll
;                     for (int u = 0; u < 16; ++u) { const f32x4* sp = (const f32x4*)(scs + (kq * 64 + kb + u) * 36);
; #pragma unroll
;                         for (int s4 = 0; s4 < 9; ++s4) { const f32x4 sv = sp[s4];
;                             acc[4 * s4 + 0] += sv[0] * w[u]; acc[4 * s4 + 1] += sv[1] * w[u]; acc[4 * s4 + 2] += sv[2] * w[u]; acc[4 * s4 + 3] += sv[3] * w[u]; } }
	v_pk_fma_f32 v[22:23], v[62:63], v[12:13], v[22:23] op_sel_hi:[0,1,1]
	v_pk_fma_f32 v[32:33], v[62:63], v[14:15], v[32:33] op_sel_hi:[0,1,1]
	ds_read_b128 v[12:15], v57 offset:1520
	s_waitcnt lgkmcnt(1)
	v_pk_fma_f32 v[34:35], v[62:63], v[8:9], v[34:35] op_sel_hi:[0,1,1]
	v_pk_fma_f32 v[36:37], v[62:63], v[10:11], v[36:37] op_sel_hi:[0,1,1]
	ds_read_b128 v[8:11], v57 offset:1536
	s_waitcnt lgkmcnt(1)
	v_pk_fma_f32 v[48:49], v[62:63], v[12:13], v[48:49] op_sel_hi:[0,1,1]
	v_pk_fma_f32 v[50:51], v[62:63], v[14:15], v[50:51] op_sel_hi:[0,1,1]
	ds_read_b128 v[12:15], v57 offset:1552
	s_waitcnt lgkmcnt(1)
	v_pk_fma_f32 v[58:59], v[62:63], v[8:9], v[58:59] op_sel_hi:[0,1,1]
	v_pk_fma_f32 v[60:61], v[62:63], v[10:11], v[60:61] op_sel_hi:[0,1,1]
	ds_read_b128 v[8:11], v57 offset:1568
	s_waitcnt lgkmcnt(1)
	v_pk_fma_f32 v[64:65], v[62:63], v[12:13], v[64:65] op_sel_hi:[0,1,1]
	v_pk_fma_f32 v[66:67], v[62:63], v[14:15], v[66:67] op_sel_hi:[0,1,1]
	ds_read_b128 v[12:15], v57 offset:1584
	s_waitcnt lgkmcnt(1)
	v_pk_fma_f32 v[28:29], v[62:63], v[8:9], v[28:29] op_sel_hi:[0,1,1]
	v_pk_fma_f32 v[30:31], v[62:63], v[10:11], v[30:31] op_sel_hi:[0,1,1]
	ds_read_b128 v[8:11], v57 offset:1600
	s_waitcnt vmcnt(3) lgkmcnt(1)
	v_pk_fma_f32 v[62:63], v[46:47], v[12:13], v[68:69] op_sel_hi:[0,1,1]
	v_pk_fma_f32 v[68:69], v[46:47], v[14:15], v[18:19] op_sel_hi:[0,1,1]
	ds_read_b128 v[12:15], v57 offset:1616
	s_waitcnt lgkmcnt(1)
	v_pk_fma_f32 v[24:25], v[46:47], v[8:9], v[24:25] op_sel_hi:[0,1,1]
	v_pk_fma_f32 v[26:27], v[46:47], v[10:11], v[26:27] op_sel_hi:[0,1,1]
	ds_read_b128 v[8:11], v57 offset:1632
	s_waitcnt lgkmcnt(1)
	v_pk_fma_f32 v[20:21], v[46:47], v[12:13], v[20:21] op_sel_hi:[0,1,1]
	v_pk_fma_f32 v[70:71], v[46:47], v[14:15], v[16:17] op_sel_hi:[0,1,1]
	ds_read_b128 v[12:15], v57 offset:1648
	s_waitcnt lgkmcnt(1)
	v_pk_fma_f32 v[22:23], v[46:47], v[8:9], v[22:23] op_sel_hi:[0,1,1]
	v_pk_fma_f32 v[32:33], v[46:47], v[10:11], v[32:33] op_sel_hi:[0,1,1]
	ds_read_b128 v[8:11], v57 offset:1664
	s_waitcnt lgkmcnt(1)
	v_pk_fma_f32 v[34:35], v[46:47], v[12:13], v[34:35] op_sel_hi:[0,1,1]
	v_pk_fma_f32 v[36:37], v[46:47], v[14:15], v[36:37] op_sel_hi:[0,1,1]
	ds_read_b128 v[12:15], v57 offset:1680
	s_waitcnt lgkmcnt(1)
	v_pk_fma_f32 v[48:49], v[46:47], v[8:9], v[48:49] op_sel_hi:[0,1,1]
	v_pk_fma_f32 v[50:51], v[46:47], v[10:11], v[50:51] op_sel_hi:[0,1,1]
	ds_read_b128 v[8:11], v57 offset:1696
	s_waitcnt lgkmcnt(1)
	v_pk_fma_f32 v[58:59], v[46:47], v[12:13], v[58:59] op_sel_hi:[0,1,1]
	v_pk_fma_f32 v[60:61], v[46:47], v[14:15], v[60:61] op_sel_hi:[0,1,1]
	ds_read_b128 v[12:15], v57 offset:1712
	s_waitcnt lgkmcnt(1)
	v_pk_fma_f32 v[64:65], v[46:47], v[8:9], v[64:65] op_sel_hi:[0,1,1]
	v_pk_fma_f32 v[66:67], v[46:47], v[10:11], v[66:67] op_sel_hi:[0,1,1]
	ds_read_b128 v[8:11], v57 offset:1728
	s_waitcnt lgkmcnt(1)
	v_pk_fma_f32 v[28:29], v[46:47], v[12:13], v[28:29] op_sel_hi:[0,1,1]
	v_pk_fma_f32 v[30:31], v[46:47], v[14:15], v[30:31] op_sel_hi:[0,1,1]
	ds_read_b128 v[12:15], v57 offset:1744
	ds_read_b128 v[16:19], v57 offset:1760
	s_waitcnt vmcnt(2) lgkmcnt(2)
	v_pk_fma_f32 v[46:47], v[6:7], v[8:9], v[62:63] op_sel_hi:[0,1,1]
	v_pk_fma_f32 v[62:63], v[6:7], v[10:11], v[68:69] op_sel_hi:[0,1,1]
	ds_read_b128 v[8:11], v57 offset:1776
	s_waitcnt lgkmcnt(2)
	v_pk_fma_f32 v[24:25], v[6:7], v[12:13], v[24:25] op_sel_hi:[0,1,1]
	v_pk_fma_f32 v[26:27], v[6:7], v[14:15], v[26:27] op_sel_hi:[0,1,1]
	ds_read_b128 v[12:15], v57 offset:1792
	s_waitcnt lgkmcnt(2)
	v_pk_fma_f32 v[20:21], v[6:7], v[16:17], v[20:21] op_sel_hi:[0,1,1]
	v_pk_fma_f32 v[68:69], v[6:7], v[18:19], v[70:71] op_sel_hi:[0,1,1]
	ds_read_b128 v[16:19], v57 offset:1808
	s_waitcnt lgkmcnt(2)
	v_pk_fma_f32 v[22:23], v[6:7], v[8:9], v[22:23] op_sel_hi:[0,1,1]
	v_pk_fma_f32 v[32:33], v[6:7], v[10:11], v[32:33] op_sel_hi:[0,1,1]
	ds_read_b128 v[8:11], v57 offset:1824
	s_waitcnt lgkmcnt(2)
	v_pk_fma_f32 v[34:35], v[6:7], v[12:13], v[34:35] op_sel_hi:[0,1,1]
	v_pk_fma_f32 v[36:37], v[6:7], v[14:15], v[36:37] op_sel_hi:[0,1,1]
	ds_read_b128 v[12:15], v57 offset:1840
	s_waitcnt lgkmcnt(2)
	v_pk_fma_f32 v[48:49], v[6:7], v[16:17], v[48:49] op_sel_hi:[0,1,1]
	v_pk_fma_f32 v[50:51], v[6:7], v[18:19], v[50:51] op_sel_hi:[0,1,1]
	ds_read_b128 v[16:19], v57 offset:1856
	s_waitcnt lgkmcnt(2)
	v_pk_fma_f32 v[58:59], v[6:7], v[8:9], v[58:59] op_sel_hi:[0,1,1]
	v_pk_fma_f32 v[60:61], v[6:7], v[10:11], v[60:61] op_sel_hi:[0,1,1]
	ds_read_b128 v[8:11], v57 offset:1872
	s_waitcnt lgkmcnt(2)
	v_pk_fma_f32 v[64:65], v[6:7], v[12:13], v[64:65] op_sel_hi:[0,1,1]
	v_pk_fma_f32 v[66:67], v[6:7], v[14:15], v[66:67] op_sel_hi:[0,1,1]
	ds_read_b128 v[12:15], v57 offset:1888
	s_waitcnt lgkmcnt(2)
	v_pk_fma_f32 v[28:29], v[6:7], v[16:17], v[28:29] op_sel_hi:[0,1,1]
	v_pk_fma_f32 v[30:31], v[6:7], v[18:19], v[30:31] op_sel_hi:[0,1,1]
	ds_read_b128 v[16:19], v57 offset:1904
	s_waitcnt vmcnt(1) lgkmcnt(2)
	v_pk_fma_f32 v[46:47], v[4:5], v[8:9], v[46:47] op_sel_hi:[0,1,1]
	ds_read_b128 v[6:9], v57 offset:1920
	v_pk_fma_f32 v[62:63], v[4:5], v[10:11], v[62:63] op_sel_hi:[0,1,1]
	s_waitcnt lgkmcnt(2)
; __device__ __forceinline__ void phase_mod(const Params& p, unsigned char* lds) {
;     ...
;                 for (int kb = 0; kb < 64; kb += 16) {
;                     float w[16];
; #pragma unroll
;                     for (int u = 0; u < 16; ++u) w[u] = __builtin_nontemporal_load(wp + (size_t)(kb + u) * 6144);
; #pragma unroll
;                     for (int u = 0; u < 16; ++u) { const f32x4* sp = (const f32x4*)(scs + (kq * 64 + kb + u) * 36);
; #pragma unroll
;                         for (int s4 = 0; s4 < 9; ++s4) { const f32x4 sv = sp[s4];
;                             acc[4 * s4 + 0] += sv[0] * w[u]; acc[4 * s4 + 1] += sv[1] * w[u]; acc[4 * s4 + 2] += sv[2] * w[u]; acc[4 * s4 + 3] += sv[3] * w[u]; } }
	v_pk_fma_f32 v[24:25], v[4:5], v[12:13], v[24:25] op_sel_hi:[0,1,1]
	v_pk_fma_f32 v[26:27], v[4:5], v[14:15], v[26:27] op_sel_hi:[0,1,1]
	ds_read_b128 v[10:13], v57 offset:1936
	s_waitcnt lgkmcnt(2)
	v_pk_fma_f32 v[70:71], v[4:5], v[16:17], v[20:21] op_sel_hi:[0,1,1]
	ds_read_b128 v[14:17], v57 offset:1952
	s_waitcnt lgkmcnt(2)
	v_pk_fma_f32 v[22:23], v[4:5], v[6:7], v[22:23] op_sel_hi:[0,1,1]
	v_pk_fma_f32 v[32:33], v[4:5], v[8:9], v[32:33] op_sel_hi:[0,1,1]
	ds_read_b128 v[6:9], v57 offset:1968
	s_waitcnt lgkmcnt(2)
	v_pk_fma_f32 v[34:35], v[4:5], v[10:11], v[34:35] op_sel_hi:[0,1,1]
	v_pk_fma_f32 v[36:37], v[4:5], v[12:13], v[36:37] op_sel_hi:[0,1,1]
	ds_read_b128 v[10:13], v57 offset:1984
	s_waitcnt lgkmcnt(2)
	v_pk_fma_f32 v[48:49], v[4:5], v[14:15], v[48:49] op_sel_hi:[0,1,1]
	v_pk_fma_f32 v[50:51], v[4:5], v[16:17], v[50:51] op_sel_hi:[0,1,1]
	ds_read_b128 v[14:17], v57 offset:2000
	s_waitcnt lgkmcnt(2)
	v_pk_fma_f32 v[58:59], v[4:5], v[6:7], v[58:59] op_sel_hi:[0,1,1]
	v_pk_fma_f32 v[60:61], v[4:5], v[8:9], v[60:61] op_sel_hi:[0,1,1]
	ds_read_b128 v[6:9], v57 offset:2016
	v_pk_fma_f32 v[68:69], v[4:5], v[18:19], v[68:69] op_sel_hi:[0,1,1]
	s_waitcnt lgkmcnt(2)
	v_pk_fma_f32 v[64:65], v[4:5], v[10:11], v[64:65] op_sel_hi:[0,1,1]
	v_pk_fma_f32 v[66:67], v[4:5], v[12:13], v[66:67] op_sel_hi:[0,1,1]
	ds_read_b128 v[10:13], v57 offset:2032
	s_waitcnt lgkmcnt(2)
	v_pk_fma_f32 v[28:29], v[4:5], v[14:15], v[28:29] op_sel_hi:[0,1,1]
	v_pk_fma_f32 v[30:31], v[4:5], v[16:17], v[30:31] op_sel_hi:[0,1,1]
	ds_read_b128 v[14:17], v57 offset:2048
	ds_read_b128 v[18:21], v57 offset:2064
	s_waitcnt vmcnt(0) lgkmcnt(3)
	v_pk_fma_f32 v[46:47], v[2:3], v[6:7], v[46:47] op_sel_hi:[0,1,1]
	ds_read_b128 v[4:7], v57 offset:2080
	v_pk_fma_f32 v[62:63], v[2:3], v[8:9], v[62:63] op_sel_hi:[0,1,1]
	s_waitcnt lgkmcnt(3)
	v_pk_fma_f32 v[24:25], v[2:3], v[10:11], v[24:25] op_sel_hi:[0,1,1]
	v_pk_fma_f32 v[72:73], v[2:3], v[12:13], v[26:27] op_sel_hi:[0,1,1]
	ds_read_b128 v[8:11], v57 offset:2096
	s_waitcnt lgkmcnt(3)
	v_pk_fma_f32 v[70:71], v[2:3], v[14:15], v[70:71] op_sel_hi:[0,1,1]
	v_pk_fma_f32 v[68:69], v[2:3], v[16:17], v[68:69] op_sel_hi:[0,1,1]
	ds_read_b128 v[12:15], v57 offset:2112
	s_waitcnt lgkmcnt(3)
	v_pk_fma_f32 v[74:75], v[2:3], v[18:19], v[22:23] op_sel_hi:[0,1,1]
	ds_read_b128 v[16:19], v57 offset:2128
	s_waitcnt lgkmcnt(3)
	v_pk_fma_f32 v[78:79], v[2:3], v[4:5], v[34:35] op_sel_hi:[0,1,1]
	v_pk_fma_f32 v[80:81], v[2:3], v[6:7], v[36:37] op_sel_hi:[0,1,1]
	ds_read_b128 v[4:7], v57 offset:2144
	v_pk_fma_f32 v[76:77], v[2:3], v[20:21], v[32:33] op_sel_hi:[0,1,1]
	s_waitcnt lgkmcnt(3)
	v_pk_fma_f32 v[82:83], v[2:3], v[8:9], v[48:49] op_sel_hi:[0,1,1]
	v_pk_fma_f32 v[50:51], v[2:3], v[10:11], v[50:51] op_sel_hi:[0,1,1]
	ds_read_b128 v[8:11], v57 offset:2160
	s_waitcnt lgkmcnt(3)
	v_pk_fma_f32 v[58:59], v[2:3], v[12:13], v[58:59] op_sel_hi:[0,1,1]
	v_pk_fma_f32 v[60:61], v[2:3], v[14:15], v[60:61] op_sel_hi:[0,1,1]
	ds_read_b128 v[12:15], v57 offset:2176
	s_waitcnt lgkmcnt(3)
	v_pk_fma_f32 v[64:65], v[2:3], v[16:17], v[64:65] op_sel_hi:[0,1,1]
	v_pk_fma_f32 v[66:67], v[2:3], v[18:19], v[66:67] op_sel_hi:[0,1,1]
	ds_read_b128 v[16:19], v57 offset:2192
	s_waitcnt lgkmcnt(3)
	v_pk_fma_f32 v[84:85], v[2:3], v[4:5], v[28:29] op_sel_hi:[0,1,1]
	v_pk_fma_f32 v[86:87], v[2:3], v[6:7], v[30:31] op_sel_hi:[0,1,1]
	ds_read_b128 v[2:5], v57 offset:2208
	s_waitcnt lgkmcnt(3)
	v_pk_fma_f32 v[34:35], v[38:39], v[8:9], v[46:47] op_sel_hi:[0,1,1]
	v_pk_fma_f32 v[36:37], v[38:39], v[10:11], v[62:63] op_sel_hi:[0,1,1]
	ds_read_b128 v[6:9], v57 offset:2224
	s_waitcnt lgkmcnt(3)
	v_pk_fma_f32 v[26:27], v[38:39], v[12:13], v[24:25] op_sel_hi:[0,1,1]
	ds_read_b128 v[30:33], v57 offset:2240
	s_waitcnt lgkmcnt(3)
	v_pk_fma_f32 v[24:25], v[38:39], v[18:19], v[68:69] op_sel_hi:[0,1,1]
	ds_read_b128 v[18:21], v57 offset:2256
	s_waitcnt lgkmcnt(3)
	v_pk_fma_f32 v[10:11], v[38:39], v[2:3], v[74:75] op_sel_hi:[0,1,1]
	v_pk_fma_f32 v[12:13], v[38:39], v[4:5], v[76:77] op_sel_hi:[0,1,1]
	ds_read_b128 v[2:5], v57 offset:2272
	ds_read_b128 v[46:49], v57 offset:2288
	v_pk_fma_f32 v[28:29], v[38:39], v[14:15], v[72:73] op_sel_hi:[0,1,1]
	v_pk_fma_f32 v[22:23], v[38:39], v[16:17], v[70:71] op_sel_hi:[0,1,1]
	s_waitcnt lgkmcnt(4)
	v_pk_fma_f32 v[14:15], v[38:39], v[6:7], v[78:79] op_sel_hi:[0,1,1]
	v_pk_fma_f32 v[16:17], v[38:39], v[8:9], v[80:81] op_sel_hi:[0,1,1]
	v_add_u32_e32 v57, 0x900, v57
	s_waitcnt lgkmcnt(3)
	v_pk_fma_f32 v[30:31], v[38:39], v[30:31], v[82:83] op_sel_hi:[0,1,1]
	v_pk_fma_f32 v[32:33], v[38:39], v[32:33], v[50:51] op_sel_hi:[0,1,1]
	s_waitcnt lgkmcnt(2)
	v_pk_fma_f32 v[18:19], v[38:39], v[18:19], v[58:59] op_sel_hi:[0,1,1]
	v_pk_fma_f32 v[20:21], v[38:39], v[20:21], v[60:61] op_sel_hi:[0,1,1]
	s_waitcnt lgkmcnt(1)
	v_pk_fma_f32 v[6:7], v[38:39], v[2:3], v[64:65] op_sel_hi:[0,1,1]
	v_pk_fma_f32 v[8:9], v[38:39], v[4:5], v[66:67] op_sel_hi:[0,1,1]
	s_waitcnt lgkmcnt(0)
	v_pk_fma_f32 v[2:3], v[38:39], v[46:47], v[84:85] op_sel_hi:[0,1,1]
	v_pk_fma_f32 v[4:5], v[38:39], v[48:49], v[86:87] op_sel_hi:[0,1,1]
	s_cbranch_scc1 .LBB0_18
